# final: scan counted waits + skip dead zeroing, split-K LDS-reduced gemm tails, XCD-aware phase-3 GEMM tile order; metadata sgpr_count made truthful
# speedup vs baseline: 1.0016x; 1.0016x over previous
amdhsa.kernels:
  - .agpr_count:     0
    .args:
      - .offset:         0
        .size:           280
        .value_kind:     by_value
      - .offset:         280
        .size:           4
        .value_kind:     by_value
      - .offset:         284
        .size:           4
        .value_kind:     by_value
      - .offset:         288
        .size:           4
        .value_kind:     hidden_block_count_x
      - .offset:         292
        .size:           4
        .value_kind:     hidden_block_count_y
      - .offset:         296
        .size:           4
        .value_kind:     hidden_block_count_z
      - .offset:         300
        .size:           2
        .value_kind:     hidden_group_size_x
      - .offset:         302
        .size:           2
        .value_kind:     hidden_group_size_y
      - .offset:         304
        .size:           2
        .value_kind:     hidden_group_size_z
      - .offset:         306
        .size:           2
        .value_kind:     hidden_remainder_x
      - .offset:         308
        .size:           2
        .value_kind:     hidden_remainder_y
      - .offset:         310
        .size:           2
        .value_kind:     hidden_remainder_z
      - .offset:         328
        .size:           8
        .value_kind:     hidden_global_offset_x
      - .offset:         336
        .size:           8
        .value_kind:     hidden_global_offset_y
      - .offset:         344
        .size:           8
        .value_kind:     hidden_global_offset_z
      - .offset:         352
        .size:           2
        .value_kind:     hidden_grid_dims
      - .offset:         376
        .size:           8
        .value_kind:     hidden_multigrid_sync_arg
      - .offset:         408
        .size:           4
        .value_kind:     hidden_dynamic_lds_size
    .group_segment_fixed_size: 0
    .kernarg_segment_align: 8
    .kernarg_segment_size: 544
    .language:       OpenCL C
    .language_version:
      - 2
      - 0
    .max_flat_workgroup_size: 512
    .name:           _Z4mega6Paramsii
    .private_segment_fixed_size: 0
    .sgpr_count:     108
    .sgpr_spill_count: 8
    .symbol:         _Z4mega6Paramsii.kd
    .uniform_work_group_size: 1
    .uses_dynamic_stack: false
    .vgpr_count:     231
    .vgpr_spill_count: 0
    .wavefront_size: 64
